# all three expert weight conversions in phase 1 (gate, up, down) use the software-pipelined loop with non-temporal source loads
# speedup vs baseline: 1.0285x; 1.0151x over previous
; #define LAS __attribute__((address_space(3)))
; __device__ __forceinline__ unsigned cvt_pk_bf16(float lo, float hi) { unsigned r; asm("v_cvt_pk_bf16_f32 %0, %1, %2" : "=v"(r) : "v"(lo), "v"(hi)); return r; }
;     const int tid = fresh_tid();
;     const int tk = K / 64, tn = (N + 63) / 64, per = tk * tn, total = batch * per;
;     for (int gi = bid; gi * 4 < total; gi += nb) {
;         f32x4 v[4][2];
; #pragma unroll
;         for (int q = 0; q < 4; ++q) { const int it = gi * 4 + q;
;             v[q][0] = (f32x4){0.f, 0.f, 0.f, 0.f}; v[q][1] = (f32x4){0.f, 0.f, 0.f, 0.f};
;             if (it < total) { const int b = it / per, r = it % per, k0 = (r / tn) * 64, n0 = (r % tn) * 64;
;                 const float* sp = src + (size_t)b * sbs + (size_t)k0 * N + n0; const int c4 = (tid & 15) * 4;
;                 if (n0 + c4 < N) { v[q][0] = *(const f32x4*)(sp + (size_t)(tid >> 4) * N + c4); v[q][1] = *(const f32x4*)(sp + (size_t)((tid >> 4) + 32) * N + c4); } } }
; #pragma unroll
;         for (int q = 0; q < 4; ++q)
; #pragma unroll
;             for (int j = 0; j < 2; ++j) { const int row = (tid >> 4) + 32 * j, c4 = (tid & 15) * 4; LAS float* tp = tile + q * (64 * 65) + row * 65 + c4;
;                 tp[0] = v[q][j][0]; tp[1] = v[q][j][1]; tp[2] = v[q][j][2]; tp[3] = v[q][j][3]; }
;         __syncthreads();
; #pragma unroll
;         for (int q = 0; q < 4; ++q) { const int it = gi * 4 + q;
;             if (it < total) { const int b = it / per, r = it % per, k0 = (r / tn) * 64, n0 = (r % tn) * 64;
;                 const int n = tid >> 3, kc = (tid & 7) * 8;
;                 if (n0 + n < N) { float f[8];
; #pragma unroll
;                     for (int j = 0; j < 8; ++j) f[j] = tile[q * (64 * 65) + (kc + j) * 65 + n];
;                     u32x4 w; w.x = cvt_pk_bf16(f[0], f[1]); w.y = cvt_pk_bf16(f[2], f[3]); w.z = cvt_pk_bf16(f[4], f[5]); w.w = cvt_pk_bf16(f[6], f[7]);
;                     int nd = n0 + n + nshift; if (nd >= N) nd -= N;
;                     *(u32x4*)(dst + (size_t)b * dbs + (size_t)nd * ldd + kofs + k0 + kc) = w; } } }
;         __syncthreads();
;     }
; __device__ void phase_convert(const Params& p, LAS unsigned char* lds) {
;     ...
;     cvt_job(tile, p.ewg, (bf16_t*)(ws + WS_WG), NE, 1024, FF, 1024, 0, (size_t)1024 * FF, (size_t)FF * 1024, (int)blockIdx.x, (int)gridDim.x);
.LBB0_667:
	v_readlane_b32 s6, v252, 10
	v_readlane_b32 s7, v252, 11
	v_mov_b32_e32 v0, v213
	s_andn2_b64 vcc, exec, s[6:7]
	v_cndmask_b32_e64 v1, 0, 1, s[6:7]
	v_cmp_ne_u32_e64 s[4:5], 1, v1
	s_cbranch_vccnz .LBB0_698
	v_lshrrev_b32_e32 v96, 4, v213
	v_and_b32_e32 v97, 15, v213
	v_lshlrev_b32_e32 v97, 4, v97
	v_mul_u32_u24_e32 v98, 0x2000, v96
	v_add_u32_e32 v98, v98, v97
	v_add_u32_e32 v99, 0x40000, v98
	v_lshrrev_b32_e32 v100, 3, v213
	v_and_b32_e32 v101, 7, v213
	v_lshlrev_b32_e32 v102, 4, v101
	v_mul_u32_u24_e32 v103, 0x800, v100
	v_add_u32_e32 v103, v103, v102
	v_mul_u32_u24_e32 v104, 0x104, v96
	v_add_u32_e32 v104, v104, v97
	v_mul_u32_u24_e32 v105, 0x820, v101
	v_lshl_add_u32 v105, v100, 2, v105
	v_mov_b32_e32 v80, v104
	v_mov_b32_e32 v88, v105
	v_add_u32_e32 v81, 0x2080, v104
	v_add_u32_e32 v89, 0x400, v105
	v_add_u32_e32 v82, 0x4100, v104
	v_add_u32_e32 v90, 0x4100, v105
	v_add_u32_e32 v83, 0x6180, v104
	v_add_u32_e32 v91, 0x4500, v105
	v_add_u32_e32 v84, 0x8200, v104
	v_add_u32_e32 v92, 0x8200, v105
	v_add_u32_e32 v85, 0xa280, v104
	v_add_u32_e32 v93, 0x8600, v105
	v_add_u32_e32 v86, 0xc300, v104
	v_add_u32_e32 v94, 0xc300, v105
	v_add_u32_e32 v87, 0xe380, v104
	v_add_u32_e32 v95, 0xc700, v105
	v_readlane_b32 s12, v252, 52
	v_readlane_b32 s13, v252, 53
	s_mov_b32 s14, s69
	s_mov_b32 s15, s84
	s_mov_b32 s20, s58
	s_lshr_b32 s16, s20, 7
	s_lshl_b32 s16, s16, 23
	s_bfe_u32 s17, s20, 0x40003
	s_lshl_b32 s17, s17, 19
	s_add_u32 s16, s16, s17
	s_and_b32 s17, s20, 7
	s_lshl_b32 s17, s17, 10
	s_add_u32 s16, s16, s17
	s_add_u32 s6, s12, s16
	s_addc_u32 s7, s13, 0
	global_load_dwordx4 v[0:3], v98, s[6:7] nt
	global_load_dwordx4 v[4:7], v99, s[6:7] nt
	global_load_dwordx4 v[8:11], v98, s[6:7] offset:256 nt
	global_load_dwordx4 v[12:15], v99, s[6:7] offset:256 nt
	global_load_dwordx4 v[16:19], v98, s[6:7] offset:512 nt
	global_load_dwordx4 v[20:23], v99, s[6:7] offset:512 nt
	global_load_dwordx4 v[24:27], v98, s[6:7] offset:768 nt
	global_load_dwordx4 v[28:31], v99, s[6:7] offset:768 nt
.Lcv_ewg_loop:
	s_lshr_b32 s16, s20, 7
	s_lshl_b32 s16, s16, 22
	s_and_b32 s17, s20, 7
	s_lshl_b32 s17, s17, 19
	s_add_u32 s16, s16, s17
	s_bfe_u32 s17, s20, 0x40003
	s_lshl_b32 s17, s17, 7
	s_add_u32 s16, s16, s17
	s_add_u32 s8, s14, s16
	s_addc_u32 s9, s15, 0
	s_waitcnt vmcnt(0)
	ds_write2_b32 v80, v0, v1 offset1:1
	ds_write2_b32 v80, v2, v3 offset0:2 offset1:3
	ds_write2_b32 v81, v4, v5 offset1:1
	ds_write2_b32 v81, v6, v7 offset0:2 offset1:3
	ds_write2_b32 v82, v8, v9 offset1:1
	ds_write2_b32 v82, v10, v11 offset0:2 offset1:3
	ds_write2_b32 v83, v12, v13 offset1:1
	ds_write2_b32 v83, v14, v15 offset0:2 offset1:3
	ds_write2_b32 v84, v16, v17 offset1:1
	ds_write2_b32 v84, v18, v19 offset0:2 offset1:3
	ds_write2_b32 v85, v20, v21 offset1:1
	ds_write2_b32 v85, v22, v23 offset0:2 offset1:3
	ds_write2_b32 v86, v24, v25 offset1:1
	ds_write2_b32 v86, v26, v27 offset0:2 offset1:3
	ds_write2_b32 v87, v28, v29 offset1:1
	ds_write2_b32 v87, v30, v31 offset0:2 offset1:3
	s_add_i32 s21, s20, s59
	s_cmpk_lt_i32 s21, 0x800
	s_cbranch_scc0 .Lcv_ewg_nopf
	s_lshr_b32 s16, s21, 7
	s_lshl_b32 s16, s16, 23
	s_bfe_u32 s17, s21, 0x40003
	s_lshl_b32 s17, s17, 19
	s_add_u32 s16, s16, s17
	s_and_b32 s17, s21, 7
	s_lshl_b32 s17, s17, 10
	s_add_u32 s16, s16, s17
	s_add_u32 s6, s12, s16
	s_addc_u32 s7, s13, 0
	global_load_dwordx4 v[0:3], v98, s[6:7] nt
	global_load_dwordx4 v[4:7], v99, s[6:7] nt
	global_load_dwordx4 v[8:11], v98, s[6:7] offset:256 nt
	global_load_dwordx4 v[12:15], v99, s[6:7] offset:256 nt
	global_load_dwordx4 v[16:19], v98, s[6:7] offset:512 nt
	global_load_dwordx4 v[20:23], v99, s[6:7] offset:512 nt
	global_load_dwordx4 v[24:27], v98, s[6:7] offset:768 nt
	global_load_dwordx4 v[28:31], v99, s[6:7] offset:768 nt
.Lcv_ewg_nopf:
	s_waitcnt lgkmcnt(0)
	s_barrier
	ds_read2_b32 v[32:33], v88 offset1:65
	ds_read2_b32 v[34:35], v88 offset0:130 offset1:195
	ds_read2_b32 v[36:37], v89 offset0:4 offset1:69
	ds_read2_b32 v[38:39], v89 offset0:134 offset1:199
	ds_read2_b32 v[40:41], v90 offset1:65
	ds_read2_b32 v[42:43], v90 offset0:130 offset1:195
	ds_read2_b32 v[44:45], v91 offset0:4 offset1:69
	ds_read2_b32 v[46:47], v91 offset0:134 offset1:199
	ds_read2_b32 v[48:49], v92 offset1:65
	ds_read2_b32 v[50:51], v92 offset0:130 offset1:195
	ds_read2_b32 v[52:53], v93 offset0:4 offset1:69
	ds_read2_b32 v[54:55], v93 offset0:134 offset1:199
	ds_read2_b32 v[56:57], v94 offset1:65
	ds_read2_b32 v[58:59], v94 offset0:130 offset1:195
	ds_read2_b32 v[60:61], v95 offset0:4 offset1:69
	ds_read2_b32 v[62:63], v95 offset0:134 offset1:199
	s_waitcnt lgkmcnt(12)
	v_cvt_pk_bf16_f32 v64, v32, v33
	v_cvt_pk_bf16_f32 v65, v34, v35
	v_cvt_pk_bf16_f32 v66, v36, v37
	v_cvt_pk_bf16_f32 v67, v38, v39
	global_store_dwordx4 v103, v[64:67], s[8:9]
	s_waitcnt lgkmcnt(8)
	v_cvt_pk_bf16_f32 v68, v40, v41
	v_cvt_pk_bf16_f32 v69, v42, v43
	v_cvt_pk_bf16_f32 v70, v44, v45
	v_cvt_pk_bf16_f32 v71, v46, v47
	s_add_u32 s10, s8, 0x20000
	s_addc_u32 s11, s9, 0
	global_store_dwordx4 v103, v[68:71], s[10:11]
	s_waitcnt lgkmcnt(4)
	v_cvt_pk_bf16_f32 v72, v48, v49
	v_cvt_pk_bf16_f32 v73, v50, v51
	v_cvt_pk_bf16_f32 v74, v52, v53
	v_cvt_pk_bf16_f32 v75, v54, v55
	s_add_u32 s10, s8, 0x40000
	s_addc_u32 s11, s9, 0
	global_store_dwordx4 v103, v[72:75], s[10:11]
	s_waitcnt lgkmcnt(0)
	v_cvt_pk_bf16_f32 v76, v56, v57
	v_cvt_pk_bf16_f32 v77, v58, v59
	v_cvt_pk_bf16_f32 v78, v60, v61
	v_cvt_pk_bf16_f32 v79, v62, v63
	s_add_u32 s10, s8, 0x60000
	s_addc_u32 s11, s9, 0
	global_store_dwordx4 v103, v[76:79], s[10:11]
	s_barrier
	s_mov_b32 s20, s21
	s_cmpk_lt_i32 s20, 0x800
	s_cbranch_scc1 .Lcv_ewg_loop

; #define LAS __attribute__((address_space(3)))
; __device__ __forceinline__ unsigned cvt_pk_bf16(float lo, float hi) { unsigned r; asm("v_cvt_pk_bf16_f32 %0, %1, %2" : "=v"(r) : "v"(lo), "v"(hi)); return r; }
;     ...
;     for (int gi = bid; gi * 4 < total; gi += nb) {
;         f32x4 v[4][2];
; #pragma unroll
;         for (int q = 0; q < 4; ++q) { const int it = gi * 4 + q;
;             v[q][0] = (f32x4){0.f, 0.f, 0.f, 0.f}; v[q][1] = (f32x4){0.f, 0.f, 0.f, 0.f};
;             if (it < total) { const int b = it / per, r = it % per, k0 = (r / tn) * 64, n0 = (r % tn) * 64;
;                 const float* sp = src + (size_t)b * sbs + (size_t)k0 * N + n0; const int c4 = (tid & 15) * 4;
;                 if (n0 + c4 < N) { v[q][0] = *(const f32x4*)(sp + (size_t)(tid >> 4) * N + c4); v[q][1] = *(const f32x4*)(sp + (size_t)((tid >> 4) + 32) * N + c4); } } }
; #pragma unroll
;         for (int q = 0; q < 4; ++q)
; #pragma unroll
;             for (int j = 0; j < 2; ++j) { const int row = (tid >> 4) + 32 * j, c4 = (tid & 15) * 4; LAS float* tp = tile + q * (64 * 65) + row * 65 + c4;
;                 tp[0] = v[q][j][0]; tp[1] = v[q][j][1]; tp[2] = v[q][j][2]; tp[3] = v[q][j][3]; }
;         __syncthreads();
; #pragma unroll
;         for (int q = 0; q < 4; ++q) { const int it = gi * 4 + q;
;             if (it < total) { const int b = it / per, r = it % per, k0 = (r / tn) * 64, n0 = (r % tn) * 64;
;                 const int n = tid >> 3, kc = (tid & 7) * 8;
;                 if (n0 + n < N) { float f[8];
; #pragma unroll
;                     for (int j = 0; j < 8; ++j) f[j] = tile[q * (64 * 65) + (kc + j) * 65 + n];
;                     u32x4 w; w.x = cvt_pk_bf16(f[0], f[1]); w.y = cvt_pk_bf16(f[2], f[3]); w.z = cvt_pk_bf16(f[4], f[5]); w.w = cvt_pk_bf16(f[6], f[7]);
;                     int nd = n0 + n + nshift; if (nd >= N) nd -= N;
;                     *(u32x4*)(dst + (size_t)b * dbs + (size_t)nd * ldd + kofs + k0 + kc) = w; } } }
;         __syncthreads();
; __device__ void phase_convert(const Params& p, LAS unsigned char* lds) {
;     ...
;     cvt_job(tile, p.ewd, (bf16_t*)(ws + WS_WD), NE, FF, 1024, FF, 0, (size_t)FF * 1024, (size_t)1024 * FF, (int)blockIdx.x, (int)gridDim.x);
.LBB0_729:
	v_mov_b32_e32 v0, v213
	s_and_b64 vcc, exec, s[4:5]
	s_cbranch_vccnz .LBB0_760
	v_lshrrev_b32_e32 v96, 4, v213
	v_and_b32_e32 v97, 15, v213
	v_lshlrev_b32_e32 v97, 4, v97
	v_mul_u32_u24_e32 v98, 0x1000, v96
	v_add_u32_e32 v98, v98, v97
	v_add_u32_e32 v99, 0x20000, v98
	v_lshrrev_b32_e32 v100, 3, v213
	v_and_b32_e32 v101, 7, v213
	v_lshlrev_b32_e32 v102, 4, v101
	v_mul_u32_u24_e32 v103, 0x1000, v100
	v_add_u32_e32 v103, v103, v102
	v_mul_u32_u24_e32 v104, 0x104, v96
	v_add_u32_e32 v104, v104, v97
	v_mul_u32_u24_e32 v105, 0x820, v101
	v_lshl_add_u32 v105, v100, 2, v105
	v_mov_b32_e32 v80, v104
	v_mov_b32_e32 v88, v105
	v_add_u32_e32 v81, 0x2080, v104
	v_add_u32_e32 v89, 0x400, v105
	v_add_u32_e32 v82, 0x4100, v104
	v_add_u32_e32 v90, 0x4100, v105
	v_add_u32_e32 v83, 0x6180, v104
	v_add_u32_e32 v91, 0x4500, v105
	v_add_u32_e32 v84, 0x8200, v104
	v_add_u32_e32 v92, 0x8200, v105
	v_add_u32_e32 v85, 0xa280, v104
	v_add_u32_e32 v93, 0x8600, v105
	v_add_u32_e32 v86, 0xc300, v104
	v_add_u32_e32 v94, 0xc300, v105
	v_add_u32_e32 v87, 0xe380, v104
	v_add_u32_e32 v95, 0xc700, v105
	s_mov_b32 s12, s76
	s_mov_b32 s13, s77
	s_mov_b32 s14, s64
	s_mov_b32 s15, s33
	s_mov_b32 s20, s58
	s_lshr_b32 s16, s20, 7
	s_lshl_b32 s16, s16, 23
	s_bfe_u32 s17, s20, 0x50002
	s_lshl_b32 s17, s17, 18
	s_add_u32 s16, s16, s17
	s_and_b32 s17, s20, 3
	s_lshl_b32 s17, s17, 10
	s_add_u32 s16, s16, s17
	s_add_u32 s6, s12, s16
	s_addc_u32 s7, s13, 0
	global_load_dwordx4 v[0:3], v98, s[6:7] nt
	global_load_dwordx4 v[4:7], v99, s[6:7] nt
	global_load_dwordx4 v[8:11], v98, s[6:7] offset:256 nt
	global_load_dwordx4 v[12:15], v99, s[6:7] offset:256 nt
	global_load_dwordx4 v[16:19], v98, s[6:7] offset:512 nt
	global_load_dwordx4 v[20:23], v99, s[6:7] offset:512 nt
	global_load_dwordx4 v[24:27], v98, s[6:7] offset:768 nt
	global_load_dwordx4 v[28:31], v99, s[6:7] offset:768 nt
.Lcv_ewd_loop:
	s_lshr_b32 s16, s20, 7
	s_lshl_b32 s16, s16, 22
	s_and_b32 s17, s20, 3
	s_lshl_b32 s17, s17, 20
	s_add_u32 s16, s16, s17
	s_bfe_u32 s17, s20, 0x50002
	s_lshl_b32 s17, s17, 7
	s_add_u32 s16, s16, s17
	s_add_u32 s8, s14, s16
	s_addc_u32 s9, s15, 0
	s_waitcnt vmcnt(0)
	ds_write2_b32 v80, v0, v1 offset1:1
	ds_write2_b32 v80, v2, v3 offset0:2 offset1:3
	ds_write2_b32 v81, v4, v5 offset1:1
	ds_write2_b32 v81, v6, v7 offset0:2 offset1:3
	ds_write2_b32 v82, v8, v9 offset1:1
	ds_write2_b32 v82, v10, v11 offset0:2 offset1:3
	ds_write2_b32 v83, v12, v13 offset1:1
	ds_write2_b32 v83, v14, v15 offset0:2 offset1:3
	ds_write2_b32 v84, v16, v17 offset1:1
	ds_write2_b32 v84, v18, v19 offset0:2 offset1:3
	ds_write2_b32 v85, v20, v21 offset1:1
	ds_write2_b32 v85, v22, v23 offset0:2 offset1:3
	ds_write2_b32 v86, v24, v25 offset1:1
	ds_write2_b32 v86, v26, v27 offset0:2 offset1:3
	ds_write2_b32 v87, v28, v29 offset1:1
	ds_write2_b32 v87, v30, v31 offset0:2 offset1:3
	s_add_i32 s21, s20, s59
	s_cmpk_lt_i32 s21, 0x800
	s_cbranch_scc0 .Lcv_ewd_nopf
	s_lshr_b32 s16, s21, 7
	s_lshl_b32 s16, s16, 23
	s_bfe_u32 s17, s21, 0x50002
	s_lshl_b32 s17, s17, 18
	s_add_u32 s16, s16, s17
	s_and_b32 s17, s21, 3
	s_lshl_b32 s17, s17, 10
	s_add_u32 s16, s16, s17
	s_add_u32 s6, s12, s16
	s_addc_u32 s7, s13, 0
	global_load_dwordx4 v[0:3], v98, s[6:7] nt
	global_load_dwordx4 v[4:7], v99, s[6:7] nt
	global_load_dwordx4 v[8:11], v98, s[6:7] offset:256 nt
	global_load_dwordx4 v[12:15], v99, s[6:7] offset:256 nt
	global_load_dwordx4 v[16:19], v98, s[6:7] offset:512 nt
	global_load_dwordx4 v[20:23], v99, s[6:7] offset:512 nt
	global_load_dwordx4 v[24:27], v98, s[6:7] offset:768 nt
	global_load_dwordx4 v[28:31], v99, s[6:7] offset:768 nt
.Lcv_ewd_nopf:
	s_waitcnt lgkmcnt(0)
	s_barrier
	ds_read2_b32 v[32:33], v88 offset1:65
	ds_read2_b32 v[34:35], v88 offset0:130 offset1:195
	ds_read2_b32 v[36:37], v89 offset0:4 offset1:69
	ds_read2_b32 v[38:39], v89 offset0:134 offset1:199
	ds_read2_b32 v[40:41], v90 offset1:65
	ds_read2_b32 v[42:43], v90 offset0:130 offset1:195
	ds_read2_b32 v[44:45], v91 offset0:4 offset1:69
	ds_read2_b32 v[46:47], v91 offset0:134 offset1:199
	ds_read2_b32 v[48:49], v92 offset1:65
	ds_read2_b32 v[50:51], v92 offset0:130 offset1:195
	ds_read2_b32 v[52:53], v93 offset0:4 offset1:69
	ds_read2_b32 v[54:55], v93 offset0:134 offset1:199
	ds_read2_b32 v[56:57], v94 offset1:65
	ds_read2_b32 v[58:59], v94 offset0:130 offset1:195
	ds_read2_b32 v[60:61], v95 offset0:4 offset1:69
	ds_read2_b32 v[62:63], v95 offset0:134 offset1:199
	s_waitcnt lgkmcnt(12)
	v_cvt_pk_bf16_f32 v64, v32, v33
	v_cvt_pk_bf16_f32 v65, v34, v35
	v_cvt_pk_bf16_f32 v66, v36, v37
	v_cvt_pk_bf16_f32 v67, v38, v39
	global_store_dwordx4 v103, v[64:67], s[8:9]
	s_waitcnt lgkmcnt(8)
	v_cvt_pk_bf16_f32 v68, v40, v41
	v_cvt_pk_bf16_f32 v69, v42, v43
	v_cvt_pk_bf16_f32 v70, v44, v45
	v_cvt_pk_bf16_f32 v71, v46, v47
	s_add_u32 s10, s8, 0x40000
	s_addc_u32 s11, s9, 0
	global_store_dwordx4 v103, v[68:71], s[10:11]
	s_waitcnt lgkmcnt(4)
	v_cvt_pk_bf16_f32 v72, v48, v49
	v_cvt_pk_bf16_f32 v73, v50, v51
	v_cvt_pk_bf16_f32 v74, v52, v53
	v_cvt_pk_bf16_f32 v75, v54, v55
	s_add_u32 s10, s8, 0x80000
	s_addc_u32 s11, s9, 0
	global_store_dwordx4 v103, v[72:75], s[10:11]
	s_waitcnt lgkmcnt(0)
	v_cvt_pk_bf16_f32 v76, v56, v57
	v_cvt_pk_bf16_f32 v77, v58, v59
	v_cvt_pk_bf16_f32 v78, v60, v61
	v_cvt_pk_bf16_f32 v79, v62, v63
	s_add_u32 s10, s8, 0xc0000
	s_addc_u32 s11, s9, 0
	global_store_dwordx4 v103, v[76:79], s[10:11]
	s_barrier
	s_mov_b32 s20, s21
	s_cmpk_lt_i32 s20, 0x800
	s_cbranch_scc1 .Lcv_ewd_loop
